# grid barrier: the agent-scope acquire (buffer_inv sc1) is issued at arrival, overlapping the arrival atomic, instead of after the release flag; workgroups only issue L1-bypassing polls while they wait
# speedup vs baseline: 1.0420x; 1.0121x over previous
.LBB0_132:
	buffer_inv sc1
	s_mov_b64 s[4:5], exec
	v_readlane_b32 s2, v247, 15
	s_lshl_b32 s2, s2, 8
	v_readlane_b32 s6, v247, 13
	v_mbcnt_lo_u32_b32 v2, s4, 0
	v_readlane_b32 s7, v247, 14
	s_add_u32 s2, s6, s2
	v_mbcnt_hi_u32_b32 v2, s5, v2
	s_addc_u32 s3, s7, 0
	v_cmp_eq_u32_e32 vcc, 0, v2
	s_and_saveexec_b64 s[6:7], vcc
	s_cbranch_execz .LBB0_134
	s_bcnt1_i32_b64 s4, s[4:5]
	v_mov_b32_e32 v4, 0x1000
	v_mov_b32_e32 v5, s4
	global_atomic_add v4, v4, v5, s[2:3] offset:1024 sc0

.LBB0_147:
	s_or_b64 exec, exec, s[6:7]
	s_waitcnt vmcnt(0)
	s_waitcnt vmcnt(0)

.LBB0_165:
	s_or_b64 exec, exec, s[4:5]
	s_mov_b64 s[4:5], exec
	v_mbcnt_lo_u32_b32 v1, s4, 0
	v_mbcnt_hi_u32_b32 v1, s5, v1
	v_cmp_eq_u32_e32 vcc, 0, v1
	s_waitcnt vmcnt(0)
	s_and_saveexec_b64 s[6:7], vcc
	s_cbranch_execz .LBB0_167
	s_bcnt1_i32_b64 s4, s[4:5]
	v_mov_b32_e32 v1, 0x2000
	v_mov_b32_e32 v2, s4
	global_atomic_add v1, v2, s[2:3] offset:1024
